# pp_v15 + RC1 next-unit operand loads (7 prefetch rows + 2 log-decay rows) issued in S0c instead of S3/S4 start
# speedup vs baseline: 1.0052x; 1.0052x over previous
.Lrc_hw:
	s_waitcnt vmcnt(4)
	v_mov_b64_e32 v[30:31], v[200:201]
	v_mov_b64_e32 v[32:33], v[202:203]
	v_mov_b64_e32 v[26:27], v[204:205]
	v_mov_b64_e32 v[28:29], v[206:207]
	v_mov_b64_e32 v[14:15], v[208:209]
	v_mov_b64_e32 v[16:17], v[210:211]
	v_mov_b64_e32 v[38:39], v[212:213]
	v_mov_b64_e32 v[40:41], v[214:215]
	v_mov_b64_e32 v[34:35], v[216:217]
	v_mov_b64_e32 v[36:37], v[218:219]
	v_mov_b64_e32 v[18:19], v[220:221]
	v_mov_b64_e32 v[20:21], v[222:223]
	v_mov_b64_e32 v[42:43], v[224:225]
	v_mov_b64_e32 v[44:45], v[226:227]
	s_lshl_b32 s0, s46, 8
	s_and_b32 s0, s0, 0x100
	s_add_i32 s47, s0, 0
	s_add_i32 s47, s47, 0x22500
	s_add_i32 s2, s47, s65
	v_add_f32_dpp v200, v6, v6 row_shr:1 row_mask:0xf bank_mask:0xf bound_ctrl:1
	v_add_f32_dpp v201, v7, v7 row_shr:1 row_mask:0xf bank_mask:0xf bound_ctrl:1
	v_add_f32_dpp v202, v8, v8 row_shr:1 row_mask:0xf bank_mask:0xf bound_ctrl:1
	v_add_f32_dpp v203, v9, v9 row_shr:1 row_mask:0xf bank_mask:0xf bound_ctrl:1
	v_add_f32_dpp v204, v2, v2 row_shr:1 row_mask:0xf bank_mask:0xf bound_ctrl:1
	v_add_f32_dpp v205, v3, v3 row_shr:1 row_mask:0xf bank_mask:0xf bound_ctrl:1
	v_add_f32_dpp v206, v4, v4 row_shr:1 row_mask:0xf bank_mask:0xf bound_ctrl:1
	v_add_f32_dpp v207, v5, v5 row_shr:1 row_mask:0xf bank_mask:0xf bound_ctrl:1
	v_add_f32_dpp v200, v200, v200 row_shr:2 row_mask:0xf bank_mask:0xf bound_ctrl:1
	v_add_f32_dpp v201, v201, v201 row_shr:2 row_mask:0xf bank_mask:0xf bound_ctrl:1
	v_add_f32_dpp v202, v202, v202 row_shr:2 row_mask:0xf bank_mask:0xf bound_ctrl:1
	v_add_f32_dpp v203, v203, v203 row_shr:2 row_mask:0xf bank_mask:0xf bound_ctrl:1
	v_add_f32_dpp v204, v204, v204 row_shr:2 row_mask:0xf bank_mask:0xf bound_ctrl:1
	v_add_f32_dpp v205, v205, v205 row_shr:2 row_mask:0xf bank_mask:0xf bound_ctrl:1
	v_add_f32_dpp v206, v206, v206 row_shr:2 row_mask:0xf bank_mask:0xf bound_ctrl:1
	v_add_f32_dpp v207, v207, v207 row_shr:2 row_mask:0xf bank_mask:0xf bound_ctrl:1
	v_add_f32_dpp v200, v200, v200 row_shr:4 row_mask:0xf bank_mask:0xf bound_ctrl:1
	v_add_f32_dpp v201, v201, v201 row_shr:4 row_mask:0xf bank_mask:0xf bound_ctrl:1
	v_add_f32_dpp v202, v202, v202 row_shr:4 row_mask:0xf bank_mask:0xf bound_ctrl:1
	v_add_f32_dpp v203, v203, v203 row_shr:4 row_mask:0xf bank_mask:0xf bound_ctrl:1
	v_add_f32_dpp v204, v204, v204 row_shr:4 row_mask:0xf bank_mask:0xf bound_ctrl:1
	v_add_f32_dpp v205, v205, v205 row_shr:4 row_mask:0xf bank_mask:0xf bound_ctrl:1
	v_add_f32_dpp v206, v206, v206 row_shr:4 row_mask:0xf bank_mask:0xf bound_ctrl:1
	v_add_f32_dpp v207, v207, v207 row_shr:4 row_mask:0xf bank_mask:0xf bound_ctrl:1
	v_add_f32_dpp v200, v200, v200 row_shr:8 row_mask:0xf bank_mask:0xf bound_ctrl:1
	v_add_f32_dpp v201, v201, v201 row_shr:8 row_mask:0xf bank_mask:0xf bound_ctrl:1
	v_add_f32_dpp v202, v202, v202 row_shr:8 row_mask:0xf bank_mask:0xf bound_ctrl:1
	v_add_f32_dpp v203, v203, v203 row_shr:8 row_mask:0xf bank_mask:0xf bound_ctrl:1
	v_add_f32_dpp v204, v204, v204 row_shr:8 row_mask:0xf bank_mask:0xf bound_ctrl:1
	v_add_f32_dpp v205, v205, v205 row_shr:8 row_mask:0xf bank_mask:0xf bound_ctrl:1
	v_add_f32_dpp v206, v206, v206 row_shr:8 row_mask:0xf bank_mask:0xf bound_ctrl:1
	v_add_f32_dpp v207, v207, v207 row_shr:8 row_mask:0xf bank_mask:0xf bound_ctrl:1
	v_mov_b32_e32 v208, v89
	v_mov_b32_e32 v209, v89
	v_mov_b32_e32 v210, v89
	v_mov_b32_e32 v211, v89
	v_mov_b32_e32 v212, v89
	v_mov_b32_e32 v213, v89
	v_mov_b32_e32 v214, v89
	v_mov_b32_e32 v215, v89
	v_mov_b32_dpp v208, v200 row_bcast:15 row_mask:0xa bank_mask:0xf
	v_mov_b32_dpp v209, v201 row_bcast:15 row_mask:0xa bank_mask:0xf
	v_mov_b32_dpp v210, v202 row_bcast:15 row_mask:0xa bank_mask:0xf
	v_mov_b32_dpp v211, v203 row_bcast:15 row_mask:0xa bank_mask:0xf
	v_mov_b32_dpp v212, v204 row_bcast:15 row_mask:0xa bank_mask:0xf
	v_mov_b32_dpp v213, v205 row_bcast:15 row_mask:0xa bank_mask:0xf
	v_mov_b32_dpp v214, v206 row_bcast:15 row_mask:0xa bank_mask:0xf
	v_mov_b32_dpp v215, v207 row_bcast:15 row_mask:0xa bank_mask:0xf
	v_add_f32_e32 v200, v200, v208
	v_add_f32_e32 v201, v201, v209
	v_add_f32_e32 v202, v202, v210
	v_add_f32_e32 v203, v203, v211
	v_add_f32_e32 v204, v204, v212
	v_add_f32_e32 v205, v205, v213
	v_add_f32_e32 v206, v206, v214
	v_add_f32_e32 v207, v207, v215
	v_mov_b32_e32 v208, v89
	v_mov_b32_e32 v209, v89
	v_mov_b32_e32 v210, v89
	v_mov_b32_e32 v211, v89
	v_mov_b32_e32 v212, v89
	v_mov_b32_e32 v213, v89
	v_mov_b32_e32 v214, v89
	v_mov_b32_e32 v215, v89
	v_mov_b32_dpp v208, v200 row_bcast:31 row_mask:0xc bank_mask:0xf
	v_mov_b32_dpp v209, v201 row_bcast:31 row_mask:0xc bank_mask:0xf
	v_mov_b32_dpp v210, v202 row_bcast:31 row_mask:0xc bank_mask:0xf
	v_mov_b32_dpp v211, v203 row_bcast:31 row_mask:0xc bank_mask:0xf
	v_mov_b32_dpp v212, v204 row_bcast:31 row_mask:0xc bank_mask:0xf
	v_mov_b32_dpp v213, v205 row_bcast:31 row_mask:0xc bank_mask:0xf
	v_mov_b32_dpp v214, v206 row_bcast:31 row_mask:0xc bank_mask:0xf
	v_mov_b32_dpp v215, v207 row_bcast:31 row_mask:0xc bank_mask:0xf
	v_add_f32_e32 v200, v200, v208
	v_add_f32_e32 v201, v201, v209
	v_add_f32_e32 v202, v202, v210
	v_add_f32_e32 v203, v203, v211
	v_add_f32_e32 v204, v204, v212
	v_add_f32_e32 v205, v205, v213
	v_add_f32_e32 v206, v206, v214
	v_add_f32_e32 v207, v207, v215
	ds_write_b32 v111, v200
	ds_write_b32 v111, v201 offset:4
	ds_write_b32 v111, v202 offset:8
	ds_write_b32 v111, v203 offset:12
	ds_write_b32 v111, v204 offset:16
	ds_write_b32 v111, v205 offset:20
	ds_write_b32 v111, v206 offset:24
	ds_write_b32 v111, v207 offset:28
	s_and_saveexec_b64 s[0:1], s[44:45]
	v_mov_b32_e32 v22, s2
	ds_write_b32 v22, v200
	ds_write_b32 v22, v201 offset:4
	ds_write_b32 v22, v202 offset:8
	ds_write_b32 v22, v203 offset:12
	ds_write_b32 v22, v204 offset:16
	ds_write_b32 v22, v205 offset:20
	ds_write_b32 v22, v206 offset:24
	ds_write_b32 v22, v207 offset:28
	s_or_b64 exec, exec, s[0:1]
	s_waitcnt vmcnt(3)
	v_and_b32_e32 v195, 0xffff0000, v30
	v_lshlrev_b32_e32 v194, 16, v30
	v_and_b32_e32 v199, 0xffff0000, v38
	v_lshlrev_b32_e32 v198, 16, v38
	s_waitcnt lgkmcnt(0)
	s_barrier
	ds_read_b128 v[82:85], v167
	ds_read_b128 v[54:57], v167 offset:16
	ds_read_b128 v[70:73], v167 offset:32
	ds_read_b128 v[50:53], v167 offset:48
	ds_read_b128 v[22:25], v167 offset:64
	ds_read_b128 v[78:81], v167 offset:96
	ds_read_b128 v[46:49], v167 offset:112
	ds_read_b128 v[74:77], v167 offset:128
	ds_read_b128 v[62:65], v167 offset:144
	ds_read_b128 v[66:69], v167 offset:160
	ds_read_b128 v[58:61], v167 offset:176
	v_pk_add_f32 v[198:199], v[198:199], v[194:195] neg_lo:[0,1] neg_hi:[0,1]
	s_waitcnt vmcnt(2)
	v_and_b32_e32 v197, 0xffff0000, v26
	v_lshlrev_b32_e32 v196, 16, v26
	s_waitcnt lgkmcnt(10)
	v_pk_fma_f32 v[82:83], v[198:199], v[82:83], v[194:195]
	v_and_b32_e32 v195, 0xffff0000, v34
	v_lshlrev_b32_e32 v194, 16, v34
	s_waitcnt vmcnt(0)
	s_cmp_eq_u32 s46, 15
	s_cbranch_scc1 .Lrc_nopf
	s_add_i32 s100, s46, 1
	s_lshl_b32 s100, s100, 2
	s_or_b32 s100, s84, s100
	s_lshl_b32 s100, s100, 6
	s_or_b32 s100, s52, s100
	s_mov_b32 s101, s53
	v_lshl_add_u64 v[228:229], s[100:101], 0, v[90:91]
	v_mad_u64_u32 v[230:231], s[100:101], v228, s64, v[94:95]
	v_mad_i32_i24 v231, v229, s64, v231
	v_lshlrev_b64 v[228:229], 10, v[228:229]
	v_lshl_add_u64 v[232:233], v[96:97], 0, v[228:229]
	global_load_dwordx4 v[200:203], v[230:231], off
	global_load_dwordx4 v[204:207], v[230:231], off offset:1024
	global_load_dwordx4 v[208:211], v[230:231], off offset:2048
	global_load_dwordx4 v[212:215], v[230:231], off offset:-3648
	global_load_dwordx4 v[216:219], v[230:231], off offset:-2624
	global_load_dwordx4 v[220:223], v[230:231], off offset:-1600
	global_load_dwordx4 v[224:227], v[232:233], off
	s_add_i32 s100, s54, 0x100
	s_mov_b32 s101, s55
	v_lshl_add_u64 v[2:3], v[92:93], 0, s[100:101]
	v_lshlrev_b64 v[2:3], 11, v[2:3]
	v_lshl_add_u64 v[6:7], v[98:99], 0, v[2:3]
	global_load_dwordx4 v[2:5], v[6:7], off offset:16
	s_nop 0
	global_load_dwordx4 v[6:9], v[6:7], off
.Lrc_nopf:
	v_and_b32_e32 v101, 0xffff0000, v42
	v_lshlrev_b32_e32 v100, 16, v42
	v_pk_add_f32 v[194:195], v[194:195], v[196:197] neg_lo:[0,1] neg_hi:[0,1]
	v_lshlrev_b32_e32 v30, 16, v27
	s_waitcnt lgkmcnt(8)
	v_pk_fma_f32 v[70:71], v[194:195], v[70:71], v[196:197]
	v_pk_add_f32 v[194:195], v[100:101], -1.0 op_sel_hi:[1,0]
	s_waitcnt lgkmcnt(5)
	v_mul_f32_e32 v78, v70, v78
	s_waitcnt lgkmcnt(3)
	v_pk_fma_f32 v[74:75], v[194:195], v[74:75], 1.0 op_sel_hi:[1,1,0]
	v_mul_f32_e32 v1, v71, v79
	v_pk_mul_f32 v[70:71], v[70:71], v[74:75]
	v_mul_f32_e32 v79, v1, v1
	v_pk_mul_f32 v[74:75], v[82:83], v[70:71]
	v_fmac_f32_e32 v79, v78, v78
	s_waitcnt lgkmcnt(1)
	v_pk_mul_f32 v[66:67], v[66:67], v[74:75]
	v_and_b32_e32 v75, 0xffff0000, v31
	v_add_f32_e32 v26, 0, v66
	v_add_f32_e32 v42, v67, v26
	v_lshlrev_b32_e32 v74, 16, v31
	v_and_b32_e32 v31, 0xffff0000, v27
	v_and_b32_e32 v27, 0xffff0000, v39
	v_lshlrev_b32_e32 v26, 16, v39
	v_pk_add_f32 v[26:27], v[26:27], v[74:75] neg_lo:[0,1] neg_hi:[0,1]
	v_and_b32_e32 v67, 0xffff0000, v43
	v_pk_fma_f32 v[38:39], v[26:27], v[84:85], v[74:75]
	v_and_b32_e32 v27, 0xffff0000, v35
	v_lshlrev_b32_e32 v26, 16, v35
	v_lshlrev_b32_e32 v66, 16, v43
	v_pk_add_f32 v[26:27], v[26:27], v[30:31] neg_lo:[0,1] neg_hi:[0,1]
	v_and_b32_e32 v43, 0xffff0000, v40
	v_pk_fma_f32 v[26:27], v[26:27], v[72:73], v[30:31]
	v_pk_add_f32 v[30:31], v[66:67], -1.0 op_sel_hi:[1,0]
	v_mul_f32_e32 v73, v26, v80
	v_pk_fma_f32 v[30:31], v[30:31], v[76:77], 1.0 op_sel_hi:[1,1,0]
	v_mul_f32_e32 v72, v27, v81
	v_pk_mul_f32 v[34:35], v[26:27], v[30:31]
	v_and_b32_e32 v31, 0xffff0000, v28
	v_pk_mul_f32 v[26:27], v[38:39], v[34:35]
	v_lshlrev_b32_e32 v30, 16, v28
	v_pk_mul_f32 v[26:27], v[68:69], v[26:27]
	v_and_b32_e32 v69, 0xffff0000, v44
	v_add_f32_e32 v26, v26, v42
	v_add_f32_e32 v74, v27, v26
	v_and_b32_e32 v27, 0xffff0000, v32
	v_lshlrev_b32_e32 v26, 16, v32
	v_lshlrev_b32_e32 v42, 16, v40
	v_pk_add_f32 v[42:43], v[42:43], v[26:27] neg_lo:[0,1] neg_hi:[0,1]
	v_lshlrev_b32_e32 v68, 16, v44
	v_pk_fma_f32 v[54:55], v[42:43], v[54:55], v[26:27]
	v_and_b32_e32 v27, 0xffff0000, v36
	v_lshlrev_b32_e32 v26, 16, v36
	v_pk_add_f32 v[26:27], v[26:27], v[30:31] neg_lo:[0,1] neg_hi:[0,1]
	v_lshlrev_b32_e32 v32, 16, v29
	v_pk_fma_f32 v[26:27], v[26:27], v[50:51], v[30:31]
	v_pk_add_f32 v[30:31], v[68:69], -1.0 op_sel_hi:[1,0]
	v_mul_f32_e32 v44, v26, v46
	v_pk_fma_f32 v[30:31], v[30:31], v[62:63], 1.0 op_sel_hi:[1,1,0]
	v_mul_f32_e32 v40, v27, v47
	v_pk_mul_f32 v[42:43], v[26:27], v[30:31]
	v_lshlrev_b32_e32 v28, 16, v41
	v_pk_mul_f32 v[26:27], v[54:55], v[42:43]
	v_and_b32_e32 v31, 0xffff0000, v45
	s_waitcnt lgkmcnt(0)
	v_pk_mul_f32 v[26:27], v[58:59], v[26:27]
	v_lshlrev_b32_e32 v30, 16, v45
	v_add_f32_e32 v26, v26, v74
	v_add_f32_e32 v36, v27, v26
	v_and_b32_e32 v27, 0xffff0000, v33
	v_lshlrev_b32_e32 v26, 16, v33
	v_and_b32_e32 v33, 0xffff0000, v29
	v_and_b32_e32 v29, 0xffff0000, v41
	v_pk_add_f32 v[28:29], v[28:29], v[26:27] neg_lo:[0,1] neg_hi:[0,1]
	v_fmac_f32_e32 v79, v73, v73
	v_pk_fma_f32 v[26:27], v[28:29], v[56:57], v[26:27]
	v_and_b32_e32 v29, 0xffff0000, v37
	v_lshlrev_b32_e32 v28, 16, v37
	v_pk_add_f32 v[28:29], v[28:29], v[32:33] neg_lo:[0,1] neg_hi:[0,1]
	v_fmac_f32_e32 v79, v72, v72
	v_pk_fma_f32 v[32:33], v[28:29], v[52:53], v[32:33]
	v_pk_add_f32 v[28:29], v[30:31], -1.0 op_sel_hi:[1,0]
	v_mul_f32_e32 v37, v32, v48
	v_pk_fma_f32 v[28:29], v[28:29], v[64:65], 1.0 op_sel_hi:[1,1,0]
	v_fmac_f32_e32 v79, v44, v44
	v_pk_mul_f32 v[28:29], v[32:33], v[28:29]
	v_fmac_f32_e32 v79, v40, v40
	v_pk_mul_f32 v[46:47], v[26:27], v[28:29]
	v_fmac_f32_e32 v79, v37, v37
	v_pk_mul_f32 v[46:47], v[60:61], v[46:47]
	v_lshl_add_u32 v88, v110, 2, s47
	v_add_f32_e32 v32, v46, v36
	v_add_f32_e32 v32, v47, v32
	ds_bpermute_b32 v41, v112, v32
	v_mul_f32_e32 v36, v33, v49
	v_fmac_f32_e32 v79, v36, v36
	ds_bpermute_b32 v33, v112, v79
	v_lshlrev_b32_e32 v58, 16, v18
	s_waitcnt lgkmcnt(1)
	v_add_f32_e32 v32, v32, v41
	ds_bpermute_b32 v45, v113, v32
	ds_read_b32 v41, v88
	ds_read_b128 v[48:51], v167 offset:80
	s_waitcnt lgkmcnt(3)
	v_add_f32_e32 v33, v79, v33
	ds_bpermute_b32 v47, v113, v33
	v_and_b32_e32 v59, 0xffff0000, v18
	s_waitcnt lgkmcnt(3)
	v_add_f32_e32 v32, v32, v45
	ds_bpermute_b32 v52, v114, v32
	v_lshlrev_b32_e32 v18, 16, v19
	s_waitcnt lgkmcnt(1)
	v_add_f32_e32 v53, v33, v47
	v_and_b32_e32 v33, 0xffff0000, v14
	v_and_b32_e32 v19, 0xffff0000, v19
	s_waitcnt lgkmcnt(0)
	v_add_f32_e32 v52, v32, v52
	v_lshlrev_b32_e32 v32, 16, v14
	v_lshlrev_b32_e32 v14, 16, v15
	v_and_b32_e32 v15, 0xffff0000, v15
	v_pk_add_f32 v[58:59], v[58:59], v[32:33] neg_lo:[0,1] neg_hi:[0,1]
	v_pk_add_f32 v[18:19], v[18:19], v[14:15] neg_lo:[0,1] neg_hi:[0,1]
	v_pk_fma_f32 v[32:33], v[58:59], v[22:23], v[32:33]
	v_pk_fma_f32 v[22:23], v[18:19], v[24:25], v[14:15]
	v_lshlrev_b32_e32 v14, 16, v16
	v_and_b32_e32 v15, 0xffff0000, v16
	v_lshlrev_b32_e32 v18, 16, v20
	v_and_b32_e32 v19, 0xffff0000, v20
	v_pk_add_f32 v[18:19], v[18:19], v[14:15] neg_lo:[0,1] neg_hi:[0,1]
	ds_read_b32 v45, v115
	ds_bpermute_b32 v56, v114, v53
	v_pk_fma_f32 v[18:19], v[18:19], v[48:49], v[14:15]
	v_lshlrev_b32_e32 v14, 16, v17
	v_and_b32_e32 v15, 0xffff0000, v17
	v_lshlrev_b32_e32 v16, 16, v21
	v_and_b32_e32 v17, 0xffff0000, v21
	v_pk_add_f32 v[16:17], v[16:17], v[14:15] neg_lo:[0,1] neg_hi:[0,1]
	v_pk_mul_f32 v[58:59], v[32:33], v[52:53] op_sel_hi:[1,0]
	v_pk_fma_f32 v[14:15], v[16:17], v[50:51], v[14:15]
	v_pk_mul_f32 v[24:25], v[22:23], v[52:53] op_sel_hi:[1,0]
	v_pk_mul_f32 v[60:61], v[18:19], v[52:53] op_sel_hi:[1,0]
	v_pk_mul_f32 v[16:17], v[14:15], v[52:53] op_sel_hi:[1,0]
	v_mov_b32_e32 v46, 0
	v_cvt_pk_bf16_f32 v48, v58, v59
	v_cvt_pk_bf16_f32 v49, v24, v25
	v_cvt_pk_bf16_f32 v50, v60, v61
	v_cvt_pk_bf16_f32 v51, v16, v17
	v_mov_b32_e32 v20, 0
	global_store_dwordx4 v[102:103], v[48:51], off
	s_and_saveexec_b64 s[0:1], s[4:5]
	s_cbranch_execz .LBB0_1055
	ds_read_b32 v16, v116
	s_waitcnt lgkmcnt(0)
	v_mul_f32_e32 v20, 0x3fb8aa3b, v16

.LBB0_1113:
	s_cmp_lg_u32 s46, 15
	s_waitcnt lgkmcnt(0)
	s_barrier
	s_cbranch_scc0 .LBB0_1115
.LBB0_1115:
	v_or_b32_e32 v14, s76, v109
	v_ashrrev_i32_e32 v15, 31, v14
	v_lshlrev_b64 v[14:15], 13, v[14:15]
	v_lshl_add_u64 v[20:21], s[66:67], 0, v[14:15]
	s_mov_b32 s2, 0
	s_mov_b64 s[76:77], -1
	s_branch .LBB0_1117
